# v127 plus nt on the layer-0 out-projection epilogue's f32 residual (x) loads, streamed once during a GEMM phase
# baseline (speedup 1.0000x reference)
.LBB0_150:
	s_add_u32 s54, s52, 0xfff80080
	s_addc_u32 s55, s53, -1
	s_add_i32 s64, 0, 0x10000
	s_cmp_eq_u32 s63, 28
	s_cselect_b32 s57, s4, s55
	s_cselect_b32 s56, s5, s54
	s_cselect_b32 s55, s37, s62
	s_cselect_b32 s54, s43, s61
	s_add_i32 s66, 0, 0x14000
	v_add_u32_e32 v146, s64, v169
	v_add_u32_e32 v176, s66, v169
	ds_read_b128 v[134:137], v146
	ds_read_b128 v[138:141], v146 offset:1024
	ds_read_b128 v[142:145], v146 offset:2048
	ds_read_b128 v[146:149], v146 offset:3072
	ds_read_b128 v[160:163], v176
	ds_read_b128 v[164:167], v176 offset:1024
	ds_read_b128 v[172:175], v176 offset:2048
	ds_read_b128 v[176:179], v176 offset:3072
	v_lshl_add_u64 v[188:189], s[52:53], 0, v[158:159]
	s_add_i32 m0, s21, 0xc000
	ds_read_b128 v[180:183], v171
	ds_read_b128 v[184:187], v171 offset:1024
	ds_read_b128 v[198:201], v171 offset:2048
	ds_read_b128 v[202:205], v171 offset:3072
	ds_read_b128 v[206:209], v171 offset:4096
	ds_read_b128 v[210:213], v171 offset:5120
	ds_read_b128 v[214:217], v171 offset:6144
	ds_read_b128 v[236:239], v171 offset:7168
	global_load_lds_dwordx4 v[188:189], off
	v_lshl_add_u64 v[188:189], s[52:53], 0, v[156:157]
	s_add_i32 m0, s21, 0xe000
	s_nop 0
	global_load_lds_dwordx4 v[188:189], off
	s_waitcnt vmcnt(8)
	s_waitcnt lgkmcnt(0)
	s_barrier
	s_setprio 1
	s_waitcnt lgkmcnt(0)
	v_mfma_f32_16x16x32_bf16 v[130:133], v[134:137], v[180:183], v[130:133]
	v_mfma_f32_16x16x32_bf16 v[126:129], v[142:145], v[180:183], v[126:129]
	v_mfma_f32_16x16x32_bf16 v[114:117], v[134:137], v[198:201], v[114:117]
	v_mfma_f32_16x16x32_bf16 v[110:113], v[142:145], v[198:201], v[110:113]
	v_mfma_f32_16x16x32_bf16 v[98:101], v[134:137], v[206:209], v[98:101]
	v_mfma_f32_16x16x32_bf16 v[94:97], v[142:145], v[206:209], v[94:97]
	v_mfma_f32_16x16x32_bf16 v[82:85], v[134:137], v[214:217], v[82:85]
	v_mfma_f32_16x16x32_bf16 v[78:81], v[142:145], v[214:217], v[78:81]
	v_mfma_f32_16x16x32_bf16 v[130:133], v[138:141], v[184:187], v[130:133]
	v_mfma_f32_16x16x32_bf16 v[126:129], v[146:149], v[184:187], v[126:129]
	v_mfma_f32_16x16x32_bf16 v[114:117], v[138:141], v[202:205], v[114:117]
	v_mfma_f32_16x16x32_bf16 v[110:113], v[146:149], v[202:205], v[110:113]
	v_mfma_f32_16x16x32_bf16 v[98:101], v[138:141], v[210:213], v[98:101]
	v_mfma_f32_16x16x32_bf16 v[94:97], v[146:149], v[210:213], v[94:97]
	v_mfma_f32_16x16x32_bf16 v[82:85], v[138:141], v[236:239], v[82:85]
	v_mfma_f32_16x16x32_bf16 v[78:81], v[146:149], v[236:239], v[78:81]
	s_setprio 0
	s_setprio 1
	v_mfma_f32_16x16x32_bf16 v[122:125], v[160:163], v[180:183], v[122:125]
	v_mfma_f32_16x16x32_bf16 v[118:121], v[172:175], v[180:183], v[118:121]
	v_mfma_f32_16x16x32_bf16 v[106:109], v[160:163], v[198:201], v[106:109]
	v_mfma_f32_16x16x32_bf16 v[102:105], v[172:175], v[198:201], v[102:105]
	v_mfma_f32_16x16x32_bf16 v[90:93], v[160:163], v[206:209], v[90:93]
	v_mfma_f32_16x16x32_bf16 v[86:89], v[172:175], v[206:209], v[86:89]
	v_mfma_f32_16x16x32_bf16 v[74:77], v[160:163], v[214:217], v[74:77]
	v_mfma_f32_16x16x32_bf16 v[70:73], v[172:175], v[214:217], v[70:73]
	v_mfma_f32_16x16x32_bf16 v[122:125], v[164:167], v[184:187], v[122:125]
	v_mfma_f32_16x16x32_bf16 v[118:121], v[176:179], v[184:187], v[118:121]
	v_mfma_f32_16x16x32_bf16 v[106:109], v[164:167], v[202:205], v[106:109]
	v_mfma_f32_16x16x32_bf16 v[102:105], v[176:179], v[202:205], v[102:105]
	v_mfma_f32_16x16x32_bf16 v[90:93], v[164:167], v[210:213], v[90:93]
	v_mfma_f32_16x16x32_bf16 v[86:89], v[176:179], v[210:213], v[86:89]
	v_mfma_f32_16x16x32_bf16 v[74:77], v[164:167], v[236:239], v[74:77]
	v_mfma_f32_16x16x32_bf16 v[70:73], v[176:179], v[236:239], v[70:73]
	s_setprio 0
	s_barrier
	s_add_i32 s64, s64, s15
	v_lshl_add_u64 v[188:189], s[54:55], 0, v[190:191]
	s_mov_b32 m0, s64
	ds_read_b128 v[180:183], v171 offset:16384
	ds_read_b128 v[184:187], v171 offset:17408
	ds_read_b128 v[198:201], v171 offset:18432
	ds_read_b128 v[202:205], v171 offset:19456
	ds_read_b128 v[206:209], v171 offset:20480
	ds_read_b128 v[210:213], v171 offset:21504
	ds_read_b128 v[214:217], v171 offset:22528
	ds_read_b128 v[236:239], v171 offset:23552
	global_load_lds_dwordx4 v[188:189], off
	s_add_i32 m0, s64, 0x2000
	s_add_u32 s64, s54, 0x80000
	v_lshl_add_u64 v[218:219], s[54:55], 0, v[154:155]
	s_addc_u32 s65, s55, 0
	s_add_i32 s66, s66, s15
	global_load_lds_dwordx4 v[218:219], off
	v_lshl_add_u64 v[240:241], s[64:65], 0, v[190:191]
	s_mov_b32 m0, s66
	v_lshl_add_u64 v[242:243], s[56:57], 0, v[152:153]
	global_load_lds_dwordx4 v[240:241], off
	v_lshl_add_u64 v[240:241], s[64:65], 0, v[154:155]
	s_add_i32 m0, s66, 0x2000
	s_nop 0
	global_load_lds_dwordx4 v[240:241], off
	v_lshl_add_u64 v[240:241], s[56:57], 0, v[150:151]
	s_mov_b32 m0, s21
	s_nop 0
	global_load_lds_dwordx4 v[240:241], off
	s_mov_b32 m0, s23
	s_nop 0
	global_load_lds_dwordx4 v[242:243], off
	s_waitcnt vmcnt(8)
	s_waitcnt lgkmcnt(0)
	s_barrier
	s_setprio 1
	s_waitcnt lgkmcnt(0)
	v_mfma_f32_16x16x32_bf16 v[66:69], v[134:137], v[180:183], v[66:69]
	v_mfma_f32_16x16x32_bf16 v[62:65], v[142:145], v[180:183], v[62:65]
	v_mfma_f32_16x16x32_bf16 v[50:53], v[134:137], v[198:201], v[50:53]
	v_mfma_f32_16x16x32_bf16 v[46:49], v[142:145], v[198:201], v[46:49]
	v_mfma_f32_16x16x32_bf16 v[34:37], v[134:137], v[206:209], v[34:37]
	v_mfma_f32_16x16x32_bf16 v[30:33], v[142:145], v[206:209], v[30:33]
	v_mfma_f32_16x16x32_bf16 v[18:21], v[134:137], v[214:217], v[18:21]
	v_mfma_f32_16x16x32_bf16 v[14:17], v[142:145], v[214:217], v[14:17]
	v_mfma_f32_16x16x32_bf16 v[66:69], v[138:141], v[184:187], v[66:69]
	v_mfma_f32_16x16x32_bf16 v[62:65], v[146:149], v[184:187], v[62:65]
	v_mfma_f32_16x16x32_bf16 v[50:53], v[138:141], v[202:205], v[50:53]
	v_mfma_f32_16x16x32_bf16 v[46:49], v[146:149], v[202:205], v[46:49]
	v_mfma_f32_16x16x32_bf16 v[34:37], v[138:141], v[210:213], v[34:37]
	v_mfma_f32_16x16x32_bf16 v[30:33], v[146:149], v[210:213], v[30:33]
	v_mfma_f32_16x16x32_bf16 v[18:21], v[138:141], v[236:239], v[18:21]
	v_mfma_f32_16x16x32_bf16 v[14:17], v[146:149], v[236:239], v[14:17]
	s_setprio 0
	s_setprio 1
	v_mfma_f32_16x16x32_bf16 v[58:61], v[160:163], v[180:183], v[58:61]
	v_mfma_f32_16x16x32_bf16 v[54:57], v[172:175], v[180:183], v[54:57]
	v_mfma_f32_16x16x32_bf16 v[42:45], v[160:163], v[198:201], v[42:45]
	v_mfma_f32_16x16x32_bf16 v[38:41], v[172:175], v[198:201], v[38:41]
	v_mfma_f32_16x16x32_bf16 v[26:29], v[160:163], v[206:209], v[26:29]
	v_mfma_f32_16x16x32_bf16 v[22:25], v[172:175], v[206:209], v[22:25]
	v_mfma_f32_16x16x32_bf16 v[10:13], v[160:163], v[214:217], v[10:13]
	v_mfma_f32_16x16x32_bf16 v[6:9], v[172:175], v[214:217], v[6:9]
	v_mfma_f32_16x16x32_bf16 v[58:61], v[164:167], v[184:187], v[58:61]
	v_mfma_f32_16x16x32_bf16 v[54:57], v[176:179], v[184:187], v[54:57]
	v_mfma_f32_16x16x32_bf16 v[42:45], v[164:167], v[202:205], v[42:45]
	v_mfma_f32_16x16x32_bf16 v[38:41], v[176:179], v[202:205], v[38:41]
	v_mfma_f32_16x16x32_bf16 v[26:29], v[164:167], v[210:213], v[26:29]
	v_mfma_f32_16x16x32_bf16 v[22:25], v[176:179], v[210:213], v[22:25]
	v_mfma_f32_16x16x32_bf16 v[10:13], v[164:167], v[236:239], v[10:13]
	v_mfma_f32_16x16x32_bf16 v[6:9], v[176:179], v[236:239], v[6:9]
	s_setprio 0
	s_barrier
	s_add_i32 s64, 0, 0x18000
	s_add_i32 s65, 0, 0x1c000
	v_add_u32_e32 v146, s64, v169
	v_add_u32_e32 v176, s65, v169
	ds_read_b128 v[134:137], v146
	ds_read_b128 v[138:141], v146 offset:1024
	ds_read_b128 v[142:145], v146 offset:2048
	ds_read_b128 v[146:149], v146 offset:3072
	ds_read_b128 v[160:163], v176
	ds_read_b128 v[164:167], v176 offset:1024
	ds_read_b128 v[172:175], v176 offset:2048
	ds_read_b128 v[176:179], v176 offset:3072
	s_add_u32 s56, s56, 0x80000
	s_addc_u32 s57, s57, 0
	s_mov_b32 m0, s26
	v_lshl_add_u64 v[244:245], s[56:57], 0, v[150:151]
	ds_read_b128 v[180:183], v171 offset:32768
	ds_read_b128 v[184:187], v171 offset:33792
	ds_read_b128 v[198:201], v171 offset:34816
	ds_read_b128 v[202:205], v171 offset:35840
	ds_read_b128 v[206:209], v171 offset:36864
	ds_read_b128 v[210:213], v171 offset:37888
	ds_read_b128 v[214:217], v171 offset:38912
	ds_read_b128 v[236:239], v171 offset:39936
	global_load_lds_dwordx4 v[244:245], off
	v_lshl_add_u64 v[244:245], s[56:57], 0, v[152:153]
	s_mov_b32 m0, s29
	s_nop 0
	global_load_lds_dwordx4 v[244:245], off
	s_waitcnt vmcnt(8)
	s_waitcnt lgkmcnt(0)
	s_barrier
	s_setprio 1
	s_waitcnt lgkmcnt(0)
	v_mfma_f32_16x16x32_bf16 v[130:133], v[134:137], v[180:183], v[130:133]
	v_mfma_f32_16x16x32_bf16 v[126:129], v[142:145], v[180:183], v[126:129]
	v_mfma_f32_16x16x32_bf16 v[114:117], v[134:137], v[198:201], v[114:117]
	v_mfma_f32_16x16x32_bf16 v[110:113], v[142:145], v[198:201], v[110:113]
	v_mfma_f32_16x16x32_bf16 v[98:101], v[134:137], v[206:209], v[98:101]
	v_mfma_f32_16x16x32_bf16 v[94:97], v[142:145], v[206:209], v[94:97]
	v_mfma_f32_16x16x32_bf16 v[82:85], v[134:137], v[214:217], v[82:85]
	v_mfma_f32_16x16x32_bf16 v[78:81], v[142:145], v[214:217], v[78:81]
	v_mfma_f32_16x16x32_bf16 v[130:133], v[138:141], v[184:187], v[130:133]
	v_mfma_f32_16x16x32_bf16 v[126:129], v[146:149], v[184:187], v[126:129]
	v_mfma_f32_16x16x32_bf16 v[114:117], v[138:141], v[202:205], v[114:117]
	v_mfma_f32_16x16x32_bf16 v[110:113], v[146:149], v[202:205], v[110:113]
	v_mfma_f32_16x16x32_bf16 v[98:101], v[138:141], v[210:213], v[98:101]
	v_mfma_f32_16x16x32_bf16 v[94:97], v[146:149], v[210:213], v[94:97]
	v_mfma_f32_16x16x32_bf16 v[82:85], v[138:141], v[236:239], v[82:85]
	v_mfma_f32_16x16x32_bf16 v[78:81], v[146:149], v[236:239], v[78:81]
	s_setprio 0
	s_setprio 1
	v_mfma_f32_16x16x32_bf16 v[122:125], v[160:163], v[180:183], v[122:125]
	v_mfma_f32_16x16x32_bf16 v[118:121], v[172:175], v[180:183], v[118:121]
	v_mfma_f32_16x16x32_bf16 v[106:109], v[160:163], v[198:201], v[106:109]
	v_mfma_f32_16x16x32_bf16 v[102:105], v[172:175], v[198:201], v[102:105]
	v_mfma_f32_16x16x32_bf16 v[90:93], v[160:163], v[206:209], v[90:93]
	v_mfma_f32_16x16x32_bf16 v[86:89], v[172:175], v[206:209], v[86:89]
	v_mfma_f32_16x16x32_bf16 v[74:77], v[160:163], v[214:217], v[74:77]
	v_mfma_f32_16x16x32_bf16 v[70:73], v[172:175], v[214:217], v[70:73]
	v_mfma_f32_16x16x32_bf16 v[122:125], v[164:167], v[184:187], v[122:125]
	v_mfma_f32_16x16x32_bf16 v[118:121], v[176:179], v[184:187], v[118:121]
	v_mfma_f32_16x16x32_bf16 v[106:109], v[164:167], v[202:205], v[106:109]
	v_mfma_f32_16x16x32_bf16 v[102:105], v[176:179], v[202:205], v[102:105]
	v_mfma_f32_16x16x32_bf16 v[90:93], v[164:167], v[210:213], v[90:93]
	v_mfma_f32_16x16x32_bf16 v[86:89], v[176:179], v[210:213], v[86:89]
	v_mfma_f32_16x16x32_bf16 v[74:77], v[164:167], v[236:239], v[74:77]
	v_mfma_f32_16x16x32_bf16 v[70:73], v[176:179], v[236:239], v[70:73]
	s_setprio 0
	s_barrier
	s_add_i32 s56, s64, s15
	v_lshl_add_u64 v[188:189], v[188:189], 0, s[30:31]
	s_mov_b32 m0, s56
	ds_read_b128 v[180:183], v171 offset:49152
	ds_read_b128 v[184:187], v171 offset:50176
	ds_read_b128 v[198:201], v171 offset:51200
	ds_read_b128 v[202:205], v171 offset:52224
	ds_read_b128 v[206:209], v171 offset:53248
	ds_read_b128 v[210:213], v171 offset:54272
	ds_read_b128 v[214:217], v171 offset:55296
	ds_read_b128 v[236:239], v171 offset:56320
	global_load_lds_dwordx4 v[188:189], off
	s_add_i32 m0, s56, 0x2000
	s_add_u32 s54, s54, 0x80080
	v_lshl_add_u64 v[188:189], v[218:219], 0, s[30:31]
	s_addc_u32 s55, s55, 0
	s_add_i32 s56, s65, s15
	global_load_lds_dwordx4 v[188:189], off
	v_lshl_add_u64 v[188:189], s[54:55], 0, v[190:191]
	s_mov_b32 m0, s56
	s_nop 0
	global_load_lds_dwordx4 v[188:189], off
	v_lshl_add_u64 v[188:189], s[54:55], 0, v[154:155]
	s_add_i32 m0, s56, 0x2000
	s_nop 0
	global_load_lds_dwordx4 v[188:189], off
	v_lshl_add_u64 v[188:189], v[240:241], 0, s[30:31]
	s_mov_b32 m0, s49
	s_nop 0
	global_load_lds_dwordx4 v[188:189], off
	v_lshl_add_u64 v[188:189], v[242:243], 0, s[30:31]
	s_mov_b32 m0, s51
	s_nop 0
	global_load_lds_dwordx4 v[188:189], off
	s_waitcnt vmcnt(8)
	s_waitcnt lgkmcnt(0)
	s_barrier
	s_setprio 1
	s_waitcnt lgkmcnt(0)
	v_mfma_f32_16x16x32_bf16 v[66:69], v[134:137], v[180:183], v[66:69]
	v_mfma_f32_16x16x32_bf16 v[62:65], v[142:145], v[180:183], v[62:65]
	v_mfma_f32_16x16x32_bf16 v[50:53], v[134:137], v[198:201], v[50:53]
	v_mfma_f32_16x16x32_bf16 v[46:49], v[142:145], v[198:201], v[46:49]
	v_mfma_f32_16x16x32_bf16 v[34:37], v[134:137], v[206:209], v[34:37]
	v_mfma_f32_16x16x32_bf16 v[30:33], v[142:145], v[206:209], v[30:33]
	v_mfma_f32_16x16x32_bf16 v[18:21], v[134:137], v[214:217], v[18:21]
	v_mfma_f32_16x16x32_bf16 v[14:17], v[142:145], v[214:217], v[14:17]
	v_mfma_f32_16x16x32_bf16 v[66:69], v[138:141], v[184:187], v[66:69]
	v_mfma_f32_16x16x32_bf16 v[62:65], v[146:149], v[184:187], v[62:65]
	v_mfma_f32_16x16x32_bf16 v[50:53], v[138:141], v[202:205], v[50:53]
	v_mfma_f32_16x16x32_bf16 v[46:49], v[146:149], v[202:205], v[46:49]
	v_mfma_f32_16x16x32_bf16 v[34:37], v[138:141], v[210:213], v[34:37]
	v_mfma_f32_16x16x32_bf16 v[30:33], v[146:149], v[210:213], v[30:33]
	v_mfma_f32_16x16x32_bf16 v[18:21], v[138:141], v[236:239], v[18:21]
	v_mfma_f32_16x16x32_bf16 v[14:17], v[146:149], v[236:239], v[14:17]
	s_setprio 0
	s_setprio 1
	v_mfma_f32_16x16x32_bf16 v[58:61], v[160:163], v[180:183], v[58:61]
	v_mfma_f32_16x16x32_bf16 v[54:57], v[172:175], v[180:183], v[54:57]
	v_mfma_f32_16x16x32_bf16 v[42:45], v[160:163], v[198:201], v[42:45]
	v_mfma_f32_16x16x32_bf16 v[38:41], v[172:175], v[198:201], v[38:41]
	v_mfma_f32_16x16x32_bf16 v[26:29], v[160:163], v[206:209], v[26:29]
	v_mfma_f32_16x16x32_bf16 v[22:25], v[172:175], v[206:209], v[22:25]
	v_mfma_f32_16x16x32_bf16 v[10:13], v[160:163], v[214:217], v[10:13]
	v_mfma_f32_16x16x32_bf16 v[6:9], v[172:175], v[214:217], v[6:9]
	v_mfma_f32_16x16x32_bf16 v[58:61], v[164:167], v[184:187], v[58:61]
	v_mfma_f32_16x16x32_bf16 v[54:57], v[176:179], v[184:187], v[54:57]
	v_mfma_f32_16x16x32_bf16 v[42:45], v[164:167], v[202:205], v[42:45]
	v_mfma_f32_16x16x32_bf16 v[38:41], v[176:179], v[202:205], v[38:41]
	v_mfma_f32_16x16x32_bf16 v[26:29], v[164:167], v[210:213], v[26:29]
	v_mfma_f32_16x16x32_bf16 v[22:25], v[176:179], v[210:213], v[22:25]
	v_mfma_f32_16x16x32_bf16 v[10:13], v[164:167], v[236:239], v[10:13]
	v_mfma_f32_16x16x32_bf16 v[6:9], v[176:179], v[236:239], v[6:9]
	s_setprio 0
	s_barrier
	s_add_i32 s63, s63, 2
	s_add_u32 s61, s61, 0x100
	s_addc_u32 s62, s62, 0
	s_add_u32 s52, s52, 0x100
	s_addc_u32 s53, s53, 0
	s_cmp_gt_u32 s63, 29
	s_cbranch_scc0 .LBB0_150
	s_load_dwordx2 s[4:5], s[70:71], 0x0
	v_lshl_add_u32 v162, s48, 8, v168
	v_lshl_or_b32 v160, s50, 8, v170
	v_ashrrev_i32_e32 v161, 31, v160
	v_ashrrev_i32_e32 v163, 31, v162
	s_waitcnt lgkmcnt(0)
	v_lshl_add_u64 v[164:165], v[160:161], 2, s[4:5]
	v_lshlrev_b64 v[134:135], 13, v[162:163]
	v_lshl_add_u64 v[134:135], v[164:165], 0, v[134:135]
	global_load_dwordx4 v[172:175], v[134:135], off offset:16 nt
	global_load_dwordx4 v[176:179], v[134:135], off nt
	global_load_dwordx4 v[180:183], v[134:135], off offset:528 nt
	global_load_dwordx4 v[184:187], v[134:135], off offset:512 nt
	v_or_b32_e32 v166, 16, v162
	v_ashrrev_i32_e32 v167, 31, v166
	v_lshlrev_b64 v[134:135], 13, v[166:167]
	v_lshl_add_u64 v[138:139], v[164:165], 0, v[134:135]
	global_load_dwordx4 v[142:145], v[138:139], off offset:16 nt
	global_load_dwordx4 v[146:149], v[138:139], off nt
	global_load_dwordx4 v[134:137], v[138:139], off offset:528 nt
	s_nop 0
	global_load_dwordx4 v[138:141], v[138:139], off offset:512 nt
	v_readlane_b32 s4, v255, 14
	v_lshlrev_b64 v[188:189], 12, v[162:163]
	v_readlane_b32 s5, v255, 15
	s_waitcnt vmcnt(0)
	v_pk_add_f32 v[174:175], v[128:129], v[174:175]
	v_pk_add_f32 v[132:133], v[132:133], v[178:179]
	v_pk_add_f32 v[130:131], v[130:131], v[176:177]
	v_pk_add_f32 v[128:129], v[126:127], v[172:173]
	v_mul_f32_e32 v126, v131, v131
	v_mul_f32_e32 v127, v133, v133
	v_fmac_f32_e32 v126, v130, v130
	v_fmac_f32_e32 v127, v132, v132
	v_add_f32_e32 v126, v126, v127
	v_mul_f32_e32 v127, v129, v129
	v_mul_f32_e32 v172, v175, v175
	v_fmac_f32_e32 v127, v128, v128
	v_fmac_f32_e32 v172, v174, v174
	v_lshl_add_u64 v[188:189], s[4:5], 0, v[188:189]
	v_add_f32_e32 v127, v127, v172
	v_lshl_add_u64 v[188:189], v[160:161], 1, v[188:189]
	v_add_f32_e32 v172, v126, v127
	v_cvt_pk_bf16_f32 v126, v130, v131
	v_cvt_pk_bf16_f32 v127, v132, v133
	v_pk_add_f32 v[124:125], v[124:125], v[186:187]
	v_pk_add_f32 v[122:123], v[122:123], v[184:185]
	v_cvt_pk_bf16_f32 v128, v128, v129
	v_cvt_pk_bf16_f32 v129, v174, v175
	global_store_dwordx4 v[188:189], v[126:129], off
	s_nop 1
	v_pk_add_f32 v[126:127], v[120:121], v[182:183]
	v_pk_add_f32 v[120:121], v[118:119], v[180:181]
	v_mul_f32_e32 v118, v123, v123
	v_mul_f32_e32 v119, v125, v125
	v_fmac_f32_e32 v118, v122, v122
	v_fmac_f32_e32 v119, v124, v124
	v_add_f32_e32 v118, v118, v119
	v_mul_f32_e32 v119, v121, v121
	v_mul_f32_e32 v128, v127, v127
	v_fmac_f32_e32 v119, v120, v120
	v_fmac_f32_e32 v128, v126, v126
	v_add_f32_e32 v119, v119, v128
	v_add_f32_e32 v118, v118, v119
	v_add_f32_e32 v128, v172, v118
	v_cvt_pk_bf16_f32 v118, v122, v123
	v_cvt_pk_bf16_f32 v119, v124, v125
	v_cvt_pk_bf16_f32 v120, v120, v121
	v_cvt_pk_bf16_f32 v121, v126, v127
	global_store_dwordx4 v[188:189], v[118:121], off offset:256
	s_nop 1
	v_and_b32_e32 v119, 64, v221
	v_xor_b32_e32 v118, 16, v221
	v_add_u32_e32 v119, 64, v119
	v_cmp_lt_i32_e32 vcc, v118, v119
	s_nop 1
	v_cndmask_b32_e32 v118, v221, v118, vcc
	v_lshlrev_b32_e32 v122, 2, v118
	ds_bpermute_b32 v118, v122, v128
	s_waitcnt lgkmcnt(0)
	v_add_f32_e32 v120, v128, v118
	v_xor_b32_e32 v118, 32, v221
	v_cmp_lt_i32_e32 vcc, v118, v119
	s_nop 1
	v_cndmask_b32_e32 v118, v221, v118, vcc
	v_lshlrev_b32_e32 v123, 2, v118
	ds_bpermute_b32 v121, v123, v120
	v_lshl_add_u64 v[118:119], v[162:163], 3, s[18:19]
	s_and_saveexec_b64 s[4:5], s[38:39]
	s_cbranch_execz .LBB0_153
	s_waitcnt lgkmcnt(0)
	v_add_f32_e32 v120, v120, v121
	v_mul_f32_e32 v120, 0x4b800000, v120
	v_trunc_f32_e32 v120, v120
	v_mul_f32_e32 v121, 0x2f800000, v120
	v_floor_f32_e32 v121, v121
	v_fmac_f32_e32 v120, 0xcf800000, v121
	v_cvt_u32_f32_e32 v120, v120
	v_cvt_u32_f32_e32 v121, v121
	global_atomic_add_x2 v[118:119], v[120:121], off

.LBB0_155:
	s_or_b64 exec, exec, s[4:5]
	v_or_b32_e32 v140, 32, v162
	v_ashrrev_i32_e32 v141, 31, v140
	s_waitcnt lgkmcnt(0)
	v_lshlrev_b64 v[102:103], 13, v[140:141]
	v_lshl_add_u64 v[102:103], v[164:165], 0, v[102:103]
	global_load_dwordx4 v[124:127], v[102:103], off nt
	global_load_dwordx4 v[128:131], v[102:103], off offset:16 nt
	global_load_dwordx4 v[132:135], v[102:103], off offset:512 nt
	global_load_dwordx4 v[136:139], v[102:103], off offset:528 nt
	v_or_b32_e32 v120, 48, v162
	v_ashrrev_i32_e32 v121, 31, v120
	v_lshlrev_b64 v[102:103], 13, v[120:121]
	v_lshl_add_u64 v[106:107], v[164:165], 0, v[102:103]
	global_load_dwordx4 v[110:113], v[106:107], off offset:16 nt
	global_load_dwordx4 v[114:117], v[106:107], off nt
	global_load_dwordx4 v[102:105], v[106:107], off offset:528 nt
	s_nop 0
	global_load_dwordx4 v[106:109], v[106:107], off offset:512 nt
	v_readlane_b32 s4, v255, 14
	v_lshlrev_b64 v[140:141], 12, v[140:141]
	v_readlane_b32 s5, v255, 15
	s_waitcnt vmcnt(7)
	v_pk_add_f32 v[100:101], v[100:101], v[126:127]
	v_pk_add_f32 v[98:99], v[98:99], v[124:125]
	s_waitcnt vmcnt(6)
	v_pk_add_f32 v[96:97], v[96:97], v[130:131]
	v_pk_add_f32 v[94:95], v[94:95], v[128:129]
	s_waitcnt vmcnt(5)
	v_pk_add_f32 v[92:93], v[92:93], v[134:135]
	v_pk_add_f32 v[90:91], v[90:91], v[132:133]
	s_waitcnt vmcnt(4)
	v_pk_add_f32 v[124:125], v[88:89], v[138:139]
	v_pk_add_f32 v[126:127], v[86:87], v[136:137]
	v_mul_f32_e32 v88, v99, v99
	v_mul_f32_e32 v89, v101, v101
	v_mul_f32_e32 v128, v95, v95
	v_mul_f32_e32 v129, v97, v97
	v_cvt_pk_bf16_f32 v86, v98, v99
	v_cvt_pk_bf16_f32 v87, v100, v101
	v_mul_f32_e32 v99, v91, v91
	v_mul_f32_e32 v101, v93, v93
	v_mul_f32_e32 v130, v127, v127
	v_mul_f32_e32 v131, v125, v125
	v_fmac_f32_e32 v88, v98, v98
	v_fmac_f32_e32 v89, v100, v100
	v_fmac_f32_e32 v128, v94, v94
	v_fmac_f32_e32 v129, v96, v96
	v_fmac_f32_e32 v99, v90, v90
	v_fmac_f32_e32 v101, v92, v92
	v_fmac_f32_e32 v130, v126, v126
	v_fmac_f32_e32 v131, v124, v124
	v_add_f32_e32 v88, v88, v89
	v_add_f32_e32 v89, v128, v129
	v_add_f32_e32 v98, v99, v101
	v_add_f32_e32 v99, v130, v131
	v_add_f32_e32 v88, v88, v89
	v_add_f32_e32 v89, v98, v99
	v_add_f32_e32 v98, v88, v89
	ds_bpermute_b32 v99, v122, v98
	v_lshl_add_u64 v[140:141], s[4:5], 0, v[140:141]
	v_lshl_add_u64 v[140:141], v[160:161], 1, v[140:141]
	v_cvt_pk_bf16_f32 v88, v94, v95
	v_cvt_pk_bf16_f32 v89, v96, v97
	global_store_dwordx4 v[140:141], v[86:89], off
	s_waitcnt lgkmcnt(0)
	s_nop 0
	v_add_f32_e32 v86, v98, v99
	ds_bpermute_b32 v87, v123, v86
	v_cvt_pk_bf16_f32 v88, v90, v91
	v_cvt_pk_bf16_f32 v89, v92, v93
	v_cvt_pk_bf16_f32 v90, v126, v127
	v_cvt_pk_bf16_f32 v91, v124, v125
	global_store_dwordx4 v[140:141], v[88:91], off offset:256
	s_and_saveexec_b64 s[4:5], s[38:39]
	s_cbranch_execz .LBB0_157
	s_waitcnt lgkmcnt(0)
	v_add_f32_e32 v86, v86, v87
	v_mul_f32_e32 v86, 0x4b800000, v86
	v_trunc_f32_e32 v86, v86
	v_mul_f32_e32 v87, 0x2f800000, v86
	v_floor_f32_e32 v87, v87
	v_fmac_f32_e32 v86, 0xcf800000, v87
	v_cvt_u32_f32_e32 v86, v86
	v_cvt_u32_f32_e32 v87, v87
	global_atomic_add_x2 v[118:119], v[86:87], off offset:256

.LBB0_159:
	s_or_b64 exec, exec, s[4:5]
	v_add_u32_e32 v104, 0x80, v162
	v_ashrrev_i32_e32 v105, 31, v104
	s_waitcnt lgkmcnt(0)
	v_lshlrev_b64 v[70:71], 13, v[104:105]
	v_lshl_add_u64 v[70:71], v[164:165], 0, v[70:71]
	global_load_dwordx4 v[88:91], v[70:71], off nt
	global_load_dwordx4 v[92:95], v[70:71], off offset:16 nt
	global_load_dwordx4 v[96:99], v[70:71], off offset:512 nt
	global_load_dwordx4 v[100:103], v[70:71], off offset:528 nt
	v_add_u32_e32 v86, 0x90, v162
	v_ashrrev_i32_e32 v87, 31, v86
	v_lshlrev_b64 v[70:71], 13, v[86:87]
	v_lshl_add_u64 v[74:75], v[164:165], 0, v[70:71]
	global_load_dwordx4 v[78:81], v[74:75], off offset:16 nt
	global_load_dwordx4 v[82:85], v[74:75], off nt
	global_load_dwordx4 v[70:73], v[74:75], off offset:528 nt
	s_nop 0
	global_load_dwordx4 v[74:77], v[74:75], off offset:512 nt
	v_readlane_b32 s4, v255, 14
	v_lshlrev_b64 v[104:105], 12, v[104:105]
	v_readlane_b32 s5, v255, 15
	s_waitcnt vmcnt(7)
	v_pk_add_f32 v[68:69], v[68:69], v[90:91]
	v_pk_add_f32 v[66:67], v[66:67], v[88:89]
	s_waitcnt vmcnt(6)
	v_pk_add_f32 v[64:65], v[64:65], v[94:95]
	v_pk_add_f32 v[62:63], v[62:63], v[92:93]
	s_waitcnt vmcnt(5)
	v_pk_add_f32 v[60:61], v[60:61], v[98:99]
	v_pk_add_f32 v[58:59], v[58:59], v[96:97]
	s_waitcnt vmcnt(4)
	v_pk_add_f32 v[88:89], v[56:57], v[102:103]
	v_pk_add_f32 v[90:91], v[54:55], v[100:101]
	v_mul_f32_e32 v56, v67, v67
	v_mul_f32_e32 v57, v69, v69
	v_mul_f32_e32 v92, v63, v63
	v_mul_f32_e32 v93, v65, v65
	v_cvt_pk_bf16_f32 v54, v66, v67
	v_cvt_pk_bf16_f32 v55, v68, v69
	v_mul_f32_e32 v67, v59, v59
	v_mul_f32_e32 v69, v61, v61
	v_mul_f32_e32 v94, v91, v91
	v_mul_f32_e32 v95, v89, v89
	v_fmac_f32_e32 v56, v66, v66
	v_fmac_f32_e32 v57, v68, v68
	v_fmac_f32_e32 v92, v62, v62
	v_fmac_f32_e32 v93, v64, v64
	v_fmac_f32_e32 v67, v58, v58
	v_fmac_f32_e32 v69, v60, v60
	v_fmac_f32_e32 v94, v90, v90
	v_fmac_f32_e32 v95, v88, v88
	v_add_f32_e32 v56, v56, v57
	v_add_f32_e32 v57, v92, v93
	v_add_f32_e32 v66, v67, v69
	v_add_f32_e32 v67, v94, v95
	v_add_f32_e32 v56, v56, v57
	v_add_f32_e32 v57, v66, v67
	v_add_f32_e32 v66, v56, v57
	ds_bpermute_b32 v67, v122, v66
	v_lshl_add_u64 v[104:105], s[4:5], 0, v[104:105]
	v_lshl_add_u64 v[104:105], v[160:161], 1, v[104:105]
	v_cvt_pk_bf16_f32 v56, v62, v63
	v_cvt_pk_bf16_f32 v57, v64, v65
	global_store_dwordx4 v[104:105], v[54:57], off
	s_waitcnt lgkmcnt(0)
	s_nop 0
	v_add_f32_e32 v54, v66, v67
	ds_bpermute_b32 v55, v123, v54
	v_cvt_pk_bf16_f32 v56, v58, v59
	v_cvt_pk_bf16_f32 v57, v60, v61
	v_cvt_pk_bf16_f32 v58, v90, v91
	v_cvt_pk_bf16_f32 v59, v88, v89
	global_store_dwordx4 v[104:105], v[56:59], off offset:256
	s_and_saveexec_b64 s[4:5], s[38:39]
	s_cbranch_execz .LBB0_161
	s_waitcnt lgkmcnt(0)
	v_add_f32_e32 v54, v54, v55
	v_mul_f32_e32 v54, 0x4b800000, v54
	v_trunc_f32_e32 v54, v54
	v_mul_f32_e32 v55, 0x2f800000, v54
	v_floor_f32_e32 v55, v55
	v_fmac_f32_e32 v54, 0xcf800000, v55
	v_cvt_u32_f32_e32 v54, v54
	v_cvt_u32_f32_e32 v55, v55
	global_atomic_add_x2 v[118:119], v[54:55], off offset:1024

.LBB0_163:
	s_or_b64 exec, exec, s[4:5]
	v_add_u32_e32 v72, 0xa0, v162
	v_ashrrev_i32_e32 v73, 31, v72
	s_waitcnt lgkmcnt(0)
	v_lshlrev_b64 v[38:39], 13, v[72:73]
	v_lshl_add_u64 v[38:39], v[164:165], 0, v[38:39]
	global_load_dwordx4 v[56:59], v[38:39], off nt
	global_load_dwordx4 v[60:63], v[38:39], off offset:16 nt
	global_load_dwordx4 v[64:67], v[38:39], off offset:512 nt
	global_load_dwordx4 v[68:71], v[38:39], off offset:528 nt
	v_add_u32_e32 v54, 0xb0, v162
	v_ashrrev_i32_e32 v55, 31, v54
	v_lshlrev_b64 v[38:39], 13, v[54:55]
	v_lshl_add_u64 v[42:43], v[164:165], 0, v[38:39]
	global_load_dwordx4 v[46:49], v[42:43], off offset:16 nt
	global_load_dwordx4 v[50:53], v[42:43], off nt
	global_load_dwordx4 v[38:41], v[42:43], off offset:528 nt
	s_nop 0
	global_load_dwordx4 v[42:45], v[42:43], off offset:512 nt
	v_readlane_b32 s4, v255, 14
	v_lshlrev_b64 v[72:73], 12, v[72:73]
	v_readlane_b32 s5, v255, 15
	s_waitcnt vmcnt(7)
	v_pk_add_f32 v[36:37], v[36:37], v[58:59]
	v_pk_add_f32 v[34:35], v[34:35], v[56:57]
	s_waitcnt vmcnt(6)
	v_pk_add_f32 v[32:33], v[32:33], v[62:63]
	v_pk_add_f32 v[30:31], v[30:31], v[60:61]
	s_waitcnt vmcnt(5)
	v_pk_add_f32 v[28:29], v[28:29], v[66:67]
	v_pk_add_f32 v[26:27], v[26:27], v[64:65]
	s_waitcnt vmcnt(4)
	v_pk_add_f32 v[56:57], v[24:25], v[70:71]
	v_pk_add_f32 v[58:59], v[22:23], v[68:69]
	v_mul_f32_e32 v24, v35, v35
	v_mul_f32_e32 v25, v37, v37
	v_mul_f32_e32 v60, v31, v31
	v_mul_f32_e32 v61, v33, v33
	v_cvt_pk_bf16_f32 v22, v34, v35
	v_cvt_pk_bf16_f32 v23, v36, v37
	v_mul_f32_e32 v35, v27, v27
	v_mul_f32_e32 v37, v29, v29
	v_mul_f32_e32 v62, v59, v59
	v_mul_f32_e32 v63, v57, v57
	v_fmac_f32_e32 v24, v34, v34
	v_fmac_f32_e32 v25, v36, v36
	v_fmac_f32_e32 v60, v30, v30
	v_fmac_f32_e32 v61, v32, v32
	v_fmac_f32_e32 v35, v26, v26
	v_fmac_f32_e32 v37, v28, v28
	v_fmac_f32_e32 v62, v58, v58
	v_fmac_f32_e32 v63, v56, v56
	v_add_f32_e32 v24, v24, v25
	v_add_f32_e32 v25, v60, v61
	v_add_f32_e32 v34, v35, v37
	v_add_f32_e32 v35, v62, v63
	v_add_f32_e32 v24, v24, v25
	v_add_f32_e32 v25, v34, v35
	v_add_f32_e32 v34, v24, v25
	ds_bpermute_b32 v35, v122, v34
	v_lshl_add_u64 v[72:73], s[4:5], 0, v[72:73]
	v_lshl_add_u64 v[72:73], v[160:161], 1, v[72:73]
	v_cvt_pk_bf16_f32 v24, v30, v31
	v_cvt_pk_bf16_f32 v25, v32, v33
	global_store_dwordx4 v[72:73], v[22:25], off
	s_waitcnt lgkmcnt(0)
	s_nop 0
	v_add_f32_e32 v22, v34, v35
	ds_bpermute_b32 v23, v123, v22
	v_cvt_pk_bf16_f32 v24, v26, v27
	v_cvt_pk_bf16_f32 v25, v28, v29
	v_cvt_pk_bf16_f32 v26, v58, v59
	v_cvt_pk_bf16_f32 v27, v56, v57
	global_store_dwordx4 v[72:73], v[24:27], off offset:256
	s_and_saveexec_b64 s[4:5], s[38:39]
	s_cbranch_execz .LBB0_165
	s_waitcnt lgkmcnt(0)
	v_add_f32_e32 v22, v22, v23
	v_mul_f32_e32 v22, 0x4b800000, v22
	v_trunc_f32_e32 v22, v22
	v_mul_f32_e32 v23, 0x2f800000, v22
	v_floor_f32_e32 v23, v23
	v_fmac_f32_e32 v22, 0xcf800000, v23
	v_cvt_u32_f32_e32 v22, v22
	v_cvt_u32_f32_e32 v23, v23
	global_atomic_add_x2 v[118:119], v[22:23], off offset:1280
